# attention A/C tile loops: QK^T MFMA section moved ahead of the conditional next-tile DMA issue block so the MFMA chain executes under the DMA issue
# baseline (speedup 1.0000x reference)
; #define LAS __attribute__((address_space(3)))
; #define MFMA32(a, b, c) __builtin_amdgcn_mfma_f32_32x32x16_bf16((a), (b), (c), 0, 0, 0)
; template <int MODE, bool UNI>
; DI void attn_compute(const bf16x8 (&qf)[4], const bf16x8 (&kf)[4], const bf16x8 (&vf)[2][2], int kt, int d00, const float* lut, float ubias, AttnSt& st,
;                      unsigned W, int win, int dmask, bool lane_sel) {
;     ...
;         for (int i = 0; i < 16; ++i) { const int ci = 16 * (i >> 3) + (i & 7); bia[i] = (MODE == 4) ? lb[16 * (23 - ci)] : lb[23 - ci]; }
;     }
;     f32x16 sx;
; #pragma unroll
;     for (int i = 0; i < 16; ++i) sx[i] = 0.f;
; #pragma unroll
;     for (int ks = 0; ks < 4; ++ks) sx = MFMA32(kf[ks], qf[ks], sx);
; template <int MODE>
; DI void attn_range(const AttnCtx& c, const bf16x8 (&qf)[4], int lo, int hi, int t0, int d00, AttnSt& st, const unsigned* maskrow, int h8, int win, int dmask, bool lane_sel) {
;     ...
;         asm volatile("s_waitcnt vmcnt(0)" ::: "memory");
;         bf16x8 kf[4], vf[2][2];
; #pragma unroll
;         for (int ks = 0; ks < 4; ++ks) kf[ks] = *(const LAS bf16x8*)(c.wl + c.kfo[ks]);
; #pragma unroll
;         for (int mt = 0; mt < 2; ++mt)
; #pragma unroll
;             for (int s = 0; s < 2; ++s) vf[mt][s] = *(const LAS bf16x8*)(c.wl + 4096 + c.vfo[mt][s]);
;         const unsigned W = Wn >> h8;
;         const int dlo = t0 - kt * 32 - 31;
;         float ub = 0.f; bool uni = false;
;         if (dlo >= 182) { const unsigned ua = __builtin_amdgcn_readfirstlane(__float_as_uint(c.lut[dlo])), ue = __builtin_amdgcn_readfirstlane(__float_as_uint(c.lut[dlo + 62])); uni = (ua == ue); ub = __uint_as_float(ua); }
;         asm volatile("s_waitcnt lgkmcnt(0)" ::: "memory");
;         if (kt < hi) { attn_dma(c, kt + 1); if (MODE == 0) Wn = maskrow[kt + 1]; }
.LBB0_322:
	s_waitcnt vmcnt(0)
	ds_read_b128 v[34:37], v214
	ds_read_b128 v[90:93], v215
	ds_read_b128 v[86:89], v216
	ds_read_b128 v[82:85], v217
	ds_read_b128 v[78:81], v218 offset:4096
	ds_read_b128 v[70:73], v218 offset:6144
	ds_read_b128 v[74:77], v219 offset:4096
	ds_read_b128 v[66:69], v219 offset:6144
	s_waitcnt lgkmcnt(0)
	s_waitcnt lgkmcnt(0)
	v_mfma_f32_32x32x16_bf16 v[34:49], v[34:37], v[62:65], 0
	v_lshrrev_b32_e32 v150, v137, v106
	v_bfe_i32 v151, v150, 4, 1
	v_bfe_i32 v152, v150, 5, 1
	v_bfe_i32 v153, v150, 6, 1
	v_mfma_f32_32x32x16_bf16 v[34:49], v[90:93], v[58:61], v[34:49]
	ds_read2_b32 v[90:91], v103 offset0:22 offset1:23
	ds_read2_b32 v[92:93], v103 offset0:20 offset1:21
	ds_read2_b32 v[106:107], v103 offset0:18 offset1:19
	ds_read2_b32 v[108:109], v103 offset0:16 offset1:17
	ds_read2_b32 v[110:111], v103 offset0:6 offset1:7
	ds_read2_b32 v[112:113], v103 offset0:4 offset1:5
	ds_read2_b32 v[146:147], v103 offset0:2 offset1:3
	ds_read2_b32 v[148:149], v103 offset1:1
	s_waitcnt lgkmcnt(0)
	v_mfma_f32_32x32x16_bf16 v[34:49], v[86:89], v[54:57], v[34:49]
	v_bfe_i32 v88, v150, 2, 1
	v_bfe_i32 v86, v150, 0, 1
	v_bfe_i32 v87, v150, 1, 1
	v_bfe_i32 v89, v150, 3, 1
	v_mfma_f32_32x32x16_bf16 v[34:49], v[82:85], v[50:53], v[34:49]
	s_cmp_ge_i32 s60, s57
	s_cbranch_scc1 .LBB0_324
	s_add_i32 s61, s60, 1
	s_and_b32 s61, s61, 3
	s_cbranch_scc1 .Lmk_skip
	global_load_dwordx4 v[224:227], v[100:101], off

; template <int MODE, bool UNI>
; DI void attn_compute(const bf16x8 (&qf)[4], const bf16x8 (&kf)[4], const bf16x8 (&vf)[2][2], int kt, int d00, const float* lut, float ubias, AttnSt& st,
;                      unsigned W, int win, int dmask, bool lane_sel) {
;     ...
;     asm volatile("s_waitcnt lgkmcnt(0)" ::: "memory");
;     float sv[16]; float mx = NEGF;
; #pragma unroll
;     for (int i = 0; i < 16; ++i) {
;         const int ci = 16 * (i >> 3) + (i & 7);
;         const int dist = d0 - ci;
;         bool v;
;         if (MODE == 0) v = ((W >> ci) & 1u) != 0u;
;         else if (MODE == 1) v = ((unsigned)dist <= (unsigned)win) && ((dist & dmask) == 0);
;         else if (MODE == 2) v = lane_sel;
;         else v = dist >= 0;
;         const float bias = UNI ? ubias : bia[i];
;         float s = fmaf(sx[i], SC2, bias);
;         if (MODE == 0) { const unsigned t = (unsigned)__builtin_amdgcn_sbfe((int)W, ci, 1);
;             s = __uint_as_float((__float_as_uint(s) & t) | (__float_as_uint(NEGF) & ~t)); }
;         else s = v ? s : NEGF;
;         sv[i] = s; mx = fmaxf(mx, s);
;     }
;     mx = fmaxf(mx, __shfl_xor(mx, 32));
;     const float mnew = fmaxf(st.m, mx);
;     const float msafe = (mnew > -1e29f) ? mnew : 0.f;
;     if (__ballot(mnew > st.m) != 0ull) {
;         const float alpha = __builtin_amdgcn_exp2f(st.m - msafe);
;         st.l *= alpha; st.m = mnew;
; #pragma unroll
;         for (int i = 0; i < 16; ++i) { st.o0[i] *= alpha; st.o1[i] *= alpha; }
;     }
.LBB0_324:
	s_waitcnt lgkmcnt(0)
	s_nop 10
	v_fmac_f32_e32 v90, 0x3e38aa3b, v35
	v_fmamk_f32 v35, v36, 0x3e38aa3b, v93
	v_fmamk_f32 v36, v38, 0x3e38aa3b, v107
	v_bitop3_b32 v83, v35, s30, v88 bitop3:0xe4
	v_fmac_f32_e32 v108, 0x3e38aa3b, v41
	v_bfe_i32 v35, v150, 7, 1
	v_fmamk_f32 v34, v34, 0x3e38aa3b, v91
	v_fmac_f32_e32 v92, 0x3e38aa3b, v37
	v_fmac_f32_e32 v106, 0x3e38aa3b, v39
	v_fmamk_f32 v37, v40, 0x3e38aa3b, v109
	v_bitop3_b32 v39, v36, s30, v151 bitop3:0xe4
	v_bitop3_b32 v40, v108, s30, v35 bitop3:0xe4
	v_fmamk_f32 v35, v42, 0x3e38aa3b, v111
	v_bfe_i32 v36, v150, 16, 1
	v_bitop3_b32 v85, v34, s30, v86 bitop3:0xe4
	v_bitop3_b32 v84, v90, s30, v87 bitop3:0xe4
	v_bitop3_b32 v41, v35, s30, v36 bitop3:0xe4
	v_fmac_f32_e32 v110, 0x3e38aa3b, v43
	v_bfe_i32 v35, v150, 17, 1
	v_bitop3_b32 v82, v92, s30, v89 bitop3:0xe4
	v_max3_f32 v34, v85, s30, v84
	v_bitop3_b32 v42, v110, s30, v35 bitop3:0xe4
	v_fmamk_f32 v35, v44, 0x3e38aa3b, v113
	v_bfe_i32 v36, v150, 18, 1
	v_bitop3_b32 v38, v106, s30, v152 bitop3:0xe4
	v_max3_f32 v34, v34, v83, v82
	v_bitop3_b32 v43, v35, s30, v36 bitop3:0xe4
	v_fmac_f32_e32 v112, 0x3e38aa3b, v45
	v_bfe_i32 v35, v150, 19, 1
	v_bitop3_b32 v37, v37, s30, v153 bitop3:0xe4
	v_max3_f32 v34, v34, v39, v38
	v_bitop3_b32 v44, v112, s30, v35 bitop3:0xe4
	v_fmamk_f32 v35, v46, 0x3e38aa3b, v147
	v_bfe_i32 v36, v150, 20, 1
	v_max3_f32 v34, v34, v37, v40
	v_bitop3_b32 v45, v35, s30, v36 bitop3:0xe4
	v_fmac_f32_e32 v146, 0x3e38aa3b, v47
	v_bfe_i32 v35, v150, 21, 1
	v_max3_f32 v34, v34, v41, v42
	v_bitop3_b32 v46, v146, s30, v35 bitop3:0xe4
	v_fmamk_f32 v35, v48, 0x3e38aa3b, v149
	v_bfe_i32 v36, v150, 22, 1
	v_max3_f32 v34, v34, v43, v44
	v_bitop3_b32 v47, v35, s30, v36 bitop3:0xe4
	v_fmac_f32_e32 v148, 0x3e38aa3b, v49
	v_bfe_i32 v35, v150, 23, 1
	v_max3_f32 v34, v34, v45, v46
	v_bitop3_b32 v35, v148, s30, v35 bitop3:0xe4
	v_max3_f32 v34, v34, v47, v35
	v_mov_b32_e32 v36, v34
	s_nop 1
	v_permlane32_swap_b32_e32 v36, v34
	s_waitcnt lgkmcnt(0)
	v_max3_f32 v34, v105, v34, v36
	v_cmp_lt_f32_e32 vcc, s12, v34
	s_nop 1
	v_cndmask_b32_e32 v36, 0, v34, vcc
	v_cmp_gt_f32_e32 vcc, v34, v105
	s_cbranch_vccz .LBB0_326
	v_sub_f32_e32 v48, v105, v36
	v_exp_f32_e32 v48, v48
	s_nop 0
	v_mul_f32_e32 v102, v102, v48
	v_pk_mul_f32 v[32:33], v[32:33], v[48:49] op_sel_hi:[1,0]
	v_pk_mul_f32 v[30:31], v[30:31], v[48:49] op_sel_hi:[1,0]
	v_pk_mul_f32 v[28:29], v[28:29], v[48:49] op_sel_hi:[1,0]
	v_pk_mul_f32 v[26:27], v[26:27], v[48:49] op_sel_hi:[1,0]
	v_pk_mul_f32 v[24:25], v[24:25], v[48:49] op_sel_hi:[1,0]
	v_pk_mul_f32 v[22:23], v[22:23], v[48:49] op_sel_hi:[1,0]
	v_pk_mul_f32 v[20:21], v[20:21], v[48:49] op_sel_hi:[1,0]
	v_pk_mul_f32 v[18:19], v[18:19], v[48:49] op_sel_hi:[1,0]
	v_pk_mul_f32 v[16:17], v[16:17], v[48:49] op_sel_hi:[1,0]
	v_pk_mul_f32 v[14:15], v[14:15], v[48:49] op_sel_hi:[1,0]
	v_pk_mul_f32 v[12:13], v[12:13], v[48:49] op_sel_hi:[1,0]
	v_pk_mul_f32 v[10:11], v[10:11], v[48:49] op_sel_hi:[1,0]
	v_pk_mul_f32 v[8:9], v[8:9], v[48:49] op_sel_hi:[1,0]
	v_pk_mul_f32 v[6:7], v[6:7], v[48:49] op_sel_hi:[1,0]
	v_pk_mul_f32 v[4:5], v[4:5], v[48:49] op_sel_hi:[1,0]
	v_pk_mul_f32 v[2:3], v[2:3], v[48:49] op_sel_hi:[1,0]
	s_branch .LBB0_327

; #define LAS __attribute__((address_space(3)))
; #define MFMA32(a, b, c) __builtin_amdgcn_mfma_f32_32x32x16_bf16((a), (b), (c), 0, 0, 0)
; template <int MODE, bool UNI>
; DI void attn_compute(const bf16x8 (&qf)[4], const bf16x8 (&kf)[4], const bf16x8 (&vf)[2][2], int kt, int d00, const float* lut, float ubias, AttnSt& st,
;                      unsigned W, int win, int dmask, bool lane_sel) {
;     ...
;         for (int i = 0; i < 16; ++i) { const int ci = 16 * (i >> 3) + (i & 7); bia[i] = (MODE == 4) ? lb[16 * (23 - ci)] : lb[23 - ci]; }
;     }
;     f32x16 sx;
; #pragma unroll
;     for (int i = 0; i < 16; ++i) sx[i] = 0.f;
; #pragma unroll
;     for (int ks = 0; ks < 4; ++ks) sx = MFMA32(kf[ks], qf[ks], sx);
; template <int MODE>
; DI void attn_range(const AttnCtx& c, const bf16x8 (&qf)[4], int lo, int hi, int t0, int d00, AttnSt& st, const unsigned* maskrow, int h8, int win, int dmask, bool lane_sel) {
;     ...
;         asm volatile("s_waitcnt vmcnt(0)" ::: "memory");
;         bf16x8 kf[4], vf[2][2];
; #pragma unroll
;         for (int ks = 0; ks < 4; ++ks) kf[ks] = *(const LAS bf16x8*)(c.wl + c.kfo[ks]);
; #pragma unroll
;         for (int mt = 0; mt < 2; ++mt)
; #pragma unroll
;             for (int s = 0; s < 2; ++s) vf[mt][s] = *(const LAS bf16x8*)(c.wl + 4096 + c.vfo[mt][s]);
;         const unsigned W = Wn >> h8;
;         const int dlo = t0 - kt * 32 - 31;
;         float ub = 0.f; bool uni = false;
;         if (dlo >= 182) { const unsigned ua = __builtin_amdgcn_readfirstlane(__float_as_uint(c.lut[dlo])), ue = __builtin_amdgcn_readfirstlane(__float_as_uint(c.lut[dlo + 62])); uni = (ua == ue); ub = __uint_as_float(ua); }
;         asm volatile("s_waitcnt lgkmcnt(0)" ::: "memory");
;         if (kt < hi) { attn_dma(c, kt + 1); if (MODE == 0) Wn = maskrow[kt + 1]; }
.LBB0_347:
	s_waitcnt vmcnt(0)
	ds_read_b128 v[50:53], v214
	ds_read_b128 v[90:93], v215
	ds_read_b128 v[94:97], v216
	ds_read_b128 v[86:89], v217
	ds_read_b128 v[82:85], v218 offset:4096
	ds_read_b128 v[6:9], v218 offset:6144
	ds_read_b128 v[10:13], v219 offset:4096
	ds_read_b128 v[2:5], v219 offset:6144
	s_waitcnt lgkmcnt(0)
	s_waitcnt lgkmcnt(0)
	v_mfma_f32_32x32x16_bf16 v[50:65], v[50:53], v[70:73], 0
	v_add_u32_e32 v0, s65, v105
	v_mfma_f32_32x32x16_bf16 v[50:65], v[90:93], v[66:69], v[50:65]
	v_mfma_f32_32x32x16_bf16 v[50:65], v[94:97], v[78:81], v[50:65]
	ds_read2_b32 v[14:15], v0 offset0:22 offset1:23
	ds_read2_b32 v[90:91], v0 offset0:20 offset1:21
	ds_read2_b32 v[92:93], v0 offset0:18 offset1:19
	ds_read2_b32 v[94:95], v0 offset0:16 offset1:17
	ds_read2_b32 v[96:97], v0 offset0:6 offset1:7
	ds_read2_b32 v[108:109], v0 offset0:4 offset1:5
	ds_read2_b32 v[110:111], v0 offset0:2 offset1:3
	ds_read2_b32 v[112:113], v0 offset1:1
	s_waitcnt lgkmcnt(0)
	v_mfma_f32_32x32x16_bf16 v[50:65], v[86:89], v[74:77], v[50:65]
	s_cmp_ge_u32 s60, s61
	s_cbranch_scc1 .LBB0_349
	s_ashr_i32 s7, s6, 31
	s_mul_i32 s66, s6, 0x1600
	s_mul_hi_i32 s67, s6, 0x1600
	s_add_u32 s66, s46, s66
	s_addc_u32 s67, s47, s67
	s_mov_b32 m0, s49
	s_nop 0
	global_load_lds_dwordx4 v116, s[66:67]
	s_mov_b32 m0, s62
	s_nop 0
	global_load_lds_dwordx4 v118, s[66:67]
	s_mov_b32 m0, s63
	s_nop 0
	global_load_lds_dwordx4 v122, s[66:67]
	s_mov_b32 m0, s53
	s_nop 0
	global_load_lds_dwordx4 v126, s[66:67]
	s_lshl_b64 s[66:67], s[6:7], 1
	s_add_u32 s68, s4, s66
	s_addc_u32 s69, s5, s67
	s_mov_b32 m0, s2
	s_nop 0
	global_load_lds_dwordx4 v114, s[68:69]
	s_mov_b32 m0, s54
	s_nop 0
	global_load_lds_dwordx4 v120, s[68:69]
	s_mov_b32 m0, s64
	s_nop 0
	global_load_lds_dwordx4 v124, s[68:69]
	s_mov_b32 m0, s55
	s_nop 0
	global_load_lds_dwordx4 v128, s[68:69]
.LBB0_349:
	s_waitcnt lgkmcnt(0)
	s_nop 10
	v_fmamk_f32 v0, v50, 0x3e38aa3b, v15
	v_fmac_f32_e32 v14, 0x3e38aa3b, v51
	v_fmamk_f32 v15, v52, 0x3e38aa3b, v91
	v_fmac_f32_e32 v90, 0x3e38aa3b, v53
	v_cndmask_b32_e64 v89, v239, v0, s[0:1]
	v_cndmask_b32_e64 v88, v239, v14, s[0:1]
	v_fmamk_f32 v50, v54, 0x3e38aa3b, v93
	v_fmac_f32_e32 v92, 0x3e38aa3b, v55
	v_cndmask_b32_e64 v87, v239, v15, s[0:1]
	v_cndmask_b32_e64 v86, v239, v90, s[0:1]
	v_max3_f32 v0, v89, s30, v88
	v_fmamk_f32 v51, v56, 0x3e38aa3b, v95
	v_fmac_f32_e32 v94, 0x3e38aa3b, v57
	v_fmac_f32_e32 v96, 0x3e38aa3b, v59
	v_fmamk_f32 v53, v60, 0x3e38aa3b, v109
	v_cndmask_b32_e64 v60, v239, v50, s[0:1]
	v_cndmask_b32_e64 v59, v239, v92, s[0:1]
	v_max3_f32 v0, v0, v87, v86
	v_fmamk_f32 v52, v58, 0x3e38aa3b, v97
	v_cndmask_b32_e64 v58, v239, v51, s[0:1]
	v_cndmask_b32_e64 v57, v239, v94, s[0:1]
	v_max3_f32 v0, v0, v60, v59
	v_cndmask_b32_e64 v51, v239, v52, s[0:1]
	v_cndmask_b32_e64 v50, v239, v96, s[0:1]
	v_max3_f32 v0, v0, v58, v57
	v_fmac_f32_e32 v108, 0x3e38aa3b, v61
	v_max3_f32 v0, v0, v51, v50
	v_cndmask_b32_e64 v52, v239, v53, s[0:1]
	v_cndmask_b32_e64 v53, v239, v108, s[0:1]
	v_fmamk_f32 v14, v62, 0x3e38aa3b, v111
	v_fmac_f32_e32 v110, 0x3e38aa3b, v63
	v_max3_f32 v0, v0, v52, v53
	v_cndmask_b32_e64 v54, v239, v14, s[0:1]
	v_cndmask_b32_e64 v55, v239, v110, s[0:1]
	v_fmamk_f32 v14, v64, 0x3e38aa3b, v113
	v_fmac_f32_e32 v112, 0x3e38aa3b, v65
	v_max3_f32 v0, v0, v54, v55
	v_cndmask_b32_e64 v56, v239, v14, s[0:1]
	v_cndmask_b32_e64 v14, v239, v112, s[0:1]
	v_max3_f32 v0, v0, v56, v14
	v_mov_b32_e32 v15, v0
	s_nop 1
	v_permlane32_swap_b32_e32 v15, v0
	s_waitcnt lgkmcnt(0)
	v_max3_f32 v0, v106, v0, v15
	v_cmp_lt_f32_e32 vcc, s12, v0
	s_nop 1
	v_cndmask_b32_e32 v15, 0, v0, vcc
	v_cmp_gt_f32_e32 vcc, v0, v106
	s_cbranch_vccz .LBB0_351
	v_sub_f32_e32 v61, v106, v15
	v_exp_f32_e32 v62, v61
	s_nop 0
	v_mul_f32_e32 v48, v48, v62
	v_pk_mul_f32 v[46:47], v[46:47], v[62:63] op_sel_hi:[1,0]
	v_pk_mul_f32 v[44:45], v[44:45], v[62:63] op_sel_hi:[1,0]
	v_pk_mul_f32 v[42:43], v[42:43], v[62:63] op_sel_hi:[1,0]
	v_pk_mul_f32 v[40:41], v[40:41], v[62:63] op_sel_hi:[1,0]
	v_pk_mul_f32 v[38:39], v[38:39], v[62:63] op_sel_hi:[1,0]
	v_pk_mul_f32 v[36:37], v[36:37], v[62:63] op_sel_hi:[1,0]
	v_pk_mul_f32 v[34:35], v[34:35], v[62:63] op_sel_hi:[1,0]
	v_pk_mul_f32 v[32:33], v[32:33], v[62:63] op_sel_hi:[1,0]
	v_pk_mul_f32 v[30:31], v[30:31], v[62:63] op_sel_hi:[1,0]
	v_pk_mul_f32 v[28:29], v[28:29], v[62:63] op_sel_hi:[1,0]
	v_pk_mul_f32 v[26:27], v[26:27], v[62:63] op_sel_hi:[1,0]
	v_pk_mul_f32 v[24:25], v[24:25], v[62:63] op_sel_hi:[1,0]
	v_pk_mul_f32 v[22:23], v[22:23], v[62:63] op_sel_hi:[1,0]
	v_pk_mul_f32 v[20:21], v[20:21], v[62:63] op_sel_hi:[1,0]
	v_pk_mul_f32 v[18:19], v[18:19], v[62:63] op_sel_hi:[1,0]
	v_pk_mul_f32 v[16:17], v[16:17], v[62:63] op_sel_hi:[1,0]
	s_branch .LBB0_352

; #define LAS __attribute__((address_space(3)))
; #define MFMA32(a, b, c) __builtin_amdgcn_mfma_f32_32x32x16_bf16((a), (b), (c), 0, 0, 0)
; template <int MODE, bool UNI>
; DI void attn_compute(const bf16x8 (&qf)[4], const bf16x8 (&kf)[4], const bf16x8 (&vf)[2][2], int kt, int d00, const float* lut, float ubias, AttnSt& st,
;                      unsigned W, int win, int dmask, bool lane_sel) {
;     ...
;         for (int i = 0; i < 16; ++i) { const int ci = 16 * (i >> 3) + (i & 7); bia[i] = (MODE == 4) ? lb[16 * (23 - ci)] : lb[23 - ci]; }
;     }
;     f32x16 sx;
; #pragma unroll
;     for (int i = 0; i < 16; ++i) sx[i] = 0.f;
; #pragma unroll
;     for (int ks = 0; ks < 4; ++ks) sx = MFMA32(kf[ks], qf[ks], sx);
; template <int MODE>
; DI void attn_range(const AttnCtx& c, const bf16x8 (&qf)[4], int lo, int hi, int t0, int d00, AttnSt& st, const unsigned* maskrow, int h8, int win, int dmask, bool lane_sel) {
;     ...
;         asm volatile("s_waitcnt vmcnt(0)" ::: "memory");
;         bf16x8 kf[4], vf[2][2];
; #pragma unroll
;         for (int ks = 0; ks < 4; ++ks) kf[ks] = *(const LAS bf16x8*)(c.wl + c.kfo[ks]);
; #pragma unroll
;         for (int mt = 0; mt < 2; ++mt)
; #pragma unroll
;             for (int s = 0; s < 2; ++s) vf[mt][s] = *(const LAS bf16x8*)(c.wl + 4096 + c.vfo[mt][s]);
;         const unsigned W = Wn >> h8;
;         const int dlo = t0 - kt * 32 - 31;
;         float ub = 0.f; bool uni = false;
;         if (dlo >= 182) { const unsigned ua = __builtin_amdgcn_readfirstlane(__float_as_uint(c.lut[dlo])), ue = __builtin_amdgcn_readfirstlane(__float_as_uint(c.lut[dlo + 62])); uni = (ua == ue); ub = __uint_as_float(ua); }
;         asm volatile("s_waitcnt lgkmcnt(0)" ::: "memory");
;         if (kt < hi) { attn_dma(c, kt + 1); if (MODE == 0) Wn = maskrow[kt + 1]; }
.LBB0_359:
	s_waitcnt vmcnt(0)
	ds_read_b128 v[50:53], v214
	ds_read_b128 v[90:93], v215
	ds_read_b128 v[94:97], v216
	ds_read_b128 v[86:89], v217
	ds_read_b128 v[82:85], v218 offset:4096
	ds_read_b128 v[6:9], v218 offset:6144
	ds_read_b128 v[10:13], v219 offset:4096
	ds_read_b128 v[2:5], v219 offset:6144
	s_waitcnt lgkmcnt(0)
	s_cmp_ge_i32 s2, s57
	s_cselect_b64 s[6:7], -1, 0
	s_waitcnt lgkmcnt(0)
	v_mfma_f32_32x32x16_bf16 v[50:65], v[50:53], v[70:73], 0
	v_cmp_lt_i32_e32 vcc, -1, v14
	v_mfma_f32_32x32x16_bf16 v[50:65], v[90:93], v[66:69], v[50:65]
	v_mfma_f32_32x32x16_bf16 v[50:65], v[94:97], v[78:81], v[50:65]
	ds_read2_b32 v[90:91], v15 offset0:22 offset1:23
	ds_read2_b32 v[92:93], v15 offset0:20 offset1:21
	ds_read2_b32 v[94:95], v15 offset0:18 offset1:19
	ds_read2_b32 v[96:97], v15 offset0:16 offset1:17
	ds_read2_b32 v[104:105], v15 offset0:6 offset1:7
	ds_read2_b32 v[106:107], v15 offset0:4 offset1:5
	ds_read2_b32 v[108:109], v15 offset0:2 offset1:3
	ds_read2_b32 v[110:111], v15 offset1:1
	s_waitcnt lgkmcnt(0)
	v_mfma_f32_32x32x16_bf16 v[50:65], v[86:89], v[74:77], v[50:65]
	s_cmp_ge_i32 s2, s57
	s_cbranch_scc1 .LBB0_361
	s_ashr_i32 s1, s0, 31
	s_mul_i32 s61, s0, 0x1600
	s_mul_hi_i32 s8, s0, 0x1600
	s_add_u32 s62, s46, s61
	s_addc_u32 s63, s47, s8
	s_mov_b32 m0, s49
	s_nop 0
	global_load_lds_dwordx4 v116, s[62:63]
	s_mov_b32 m0, s9
	s_nop 0
	global_load_lds_dwordx4 v118, s[62:63]
	s_mov_b32 m0, s58
	s_nop 0
	global_load_lds_dwordx4 v122, s[62:63]
	s_mov_b32 m0, s53
	s_nop 0
	global_load_lds_dwordx4 v126, s[62:63]
	s_lshl_b64 s[62:63], s[0:1], 1
	s_add_u32 s64, s4, s62
	s_addc_u32 s65, s5, s63
	s_mov_b32 m0, s59
	s_nop 0
	global_load_lds_dwordx4 v114, s[64:65]
	s_mov_b32 m0, s54
	s_nop 0
	global_load_lds_dwordx4 v120, s[64:65]
	s_mov_b32 m0, s60
	s_nop 0
	global_load_lds_dwordx4 v124, s[64:65]
	s_mov_b32 m0, s55
	s_nop 0
	global_load_lds_dwordx4 v128, s[64:65]
.LBB0_361:
	s_waitcnt lgkmcnt(0)
	s_nop 10
	v_fmamk_f32 v49, v50, 0x3e38aa3b, v91
	v_fmac_f32_e32 v90, 0x3e38aa3b, v51
	v_fmamk_f32 v51, v54, 0x3e38aa3b, v95
	v_cndmask_b32_e32 v54, v239, v49, vcc
	v_cmp_lt_i32_e32 vcc, 0, v14
	v_fmamk_f32 v50, v52, 0x3e38aa3b, v93
	v_fmac_f32_e32 v94, 0x3e38aa3b, v55
	v_cndmask_b32_e32 v55, v239, v90, vcc
	v_cmp_lt_i32_e32 vcc, 1, v14
	v_fmac_f32_e32 v92, 0x3e38aa3b, v53
	v_fmamk_f32 v53, v56, 0x3e38aa3b, v97
	v_cndmask_b32_e32 v56, v239, v50, vcc
	v_cmp_lt_i32_e32 vcc, 2, v14
	v_fmac_f32_e32 v96, 0x3e38aa3b, v57
	v_fmac_f32_e32 v104, 0x3e38aa3b, v59
	v_cndmask_b32_e32 v50, v239, v92, vcc
	v_cmp_lt_i32_e32 vcc, 3, v14
	v_max3_f32 v49, v54, s30, v55
	v_max3_f32 v49, v49, v56, v50
	v_cndmask_b32_e32 v51, v239, v51, vcc
	v_cmp_lt_i32_e32 vcc, 4, v14
	v_fmac_f32_e32 v106, 0x3e38aa3b, v61
	v_fmac_f32_e32 v108, 0x3e38aa3b, v63
	v_cndmask_b32_e32 v52, v239, v94, vcc
	v_cmp_lt_i32_e32 vcc, 5, v14
	v_max3_f32 v49, v49, v51, v52
	v_fmac_f32_e32 v110, 0x3e38aa3b, v65
	v_cndmask_b32_e32 v86, v239, v53, vcc
	v_cmp_lt_i32_e32 vcc, 6, v14
	v_fmamk_f32 v53, v58, 0x3e38aa3b, v105
	s_nop 0
	v_cndmask_b32_e32 v87, v239, v96, vcc
	v_cmp_lt_i32_e32 vcc, 15, v14
	v_max3_f32 v49, v49, v86, v87
	s_nop 0
	v_cndmask_b32_e32 v58, v239, v53, vcc
	v_cmp_lt_i32_e32 vcc, 16, v14
	v_fmamk_f32 v53, v60, 0x3e38aa3b, v107
	s_nop 0
	v_cndmask_b32_e32 v59, v239, v104, vcc
	v_cmp_lt_i32_e32 vcc, 17, v14
	v_max3_f32 v49, v49, v58, v59
	s_nop 0
	v_cndmask_b32_e32 v60, v239, v53, vcc
	v_cmp_lt_i32_e32 vcc, 18, v14
	v_fmamk_f32 v53, v62, 0x3e38aa3b, v109
	s_nop 0
	v_cndmask_b32_e32 v61, v239, v106, vcc
	v_cmp_lt_i32_e32 vcc, 19, v14
	v_max3_f32 v49, v49, v60, v61
	s_nop 0
	v_cndmask_b32_e32 v62, v239, v53, vcc
	v_cmp_lt_i32_e32 vcc, 20, v14
	v_fmamk_f32 v53, v64, 0x3e38aa3b, v111
	s_nop 0
	v_cndmask_b32_e32 v63, v239, v108, vcc
	v_cmp_lt_i32_e32 vcc, 21, v14
	v_max3_f32 v49, v49, v62, v63
	s_nop 0
	v_cndmask_b32_e32 v64, v239, v53, vcc
	v_cmp_lt_i32_e32 vcc, 22, v14
	s_nop 1
	v_cndmask_b32_e32 v53, v239, v110, vcc
	v_max3_f32 v49, v49, v64, v53
	v_mov_b32_e32 v57, v49
	s_nop 1
	v_permlane32_swap_b32_e32 v57, v49
	s_waitcnt lgkmcnt(0)
	v_max3_f32 v49, v0, v49, v57
	v_cmp_lt_f32_e32 vcc, s12, v49
	s_nop 1
	v_cndmask_b32_e32 v57, 0, v49, vcc
	v_cmp_gt_f32_e32 vcc, v49, v0
	s_cbranch_vccz .LBB0_363
	v_sub_f32_e32 v0, v0, v57
	v_exp_f32_e32 v0, v0
	s_nop 0
	v_mul_f32_e32 v48, v48, v0
	v_pk_mul_f32 v[46:47], v[46:47], v[0:1] op_sel_hi:[1,0]
	v_pk_mul_f32 v[44:45], v[44:45], v[0:1] op_sel_hi:[1,0]
	v_pk_mul_f32 v[42:43], v[42:43], v[0:1] op_sel_hi:[1,0]
	v_pk_mul_f32 v[40:41], v[40:41], v[0:1] op_sel_hi:[1,0]
	v_pk_mul_f32 v[38:39], v[38:39], v[0:1] op_sel_hi:[1,0]
	v_pk_mul_f32 v[36:37], v[36:37], v[0:1] op_sel_hi:[1,0]
	v_pk_mul_f32 v[34:35], v[34:35], v[0:1] op_sel_hi:[1,0]
	v_pk_mul_f32 v[32:33], v[32:33], v[0:1] op_sel_hi:[1,0]
	v_pk_mul_f32 v[30:31], v[30:31], v[0:1] op_sel_hi:[1,0]
	v_pk_mul_f32 v[28:29], v[28:29], v[0:1] op_sel_hi:[1,0]
	v_pk_mul_f32 v[26:27], v[26:27], v[0:1] op_sel_hi:[1,0]
	v_pk_mul_f32 v[24:25], v[24:25], v[0:1] op_sel_hi:[1,0]
	v_pk_mul_f32 v[22:23], v[22:23], v[0:1] op_sel_hi:[1,0]
	v_pk_mul_f32 v[20:21], v[20:21], v[0:1] op_sel_hi:[1,0]
	v_pk_mul_f32 v[18:19], v[18:19], v[0:1] op_sel_hi:[1,0]
	v_pk_mul_f32 v[16:17], v[16:17], v[0:1] op_sel_hi:[1,0]
	s_branch .LBB0_364
